# strategy 4: one static s_setprio 1 for the second-slot workgroup of each CU (j^16 pairing) in the hand-written FFN-up / FFN-down / out-proj phases
# baseline (speedup 1.0000x reference)
.LBB0_259:
	s_andn2_b64 vcc, exec, s[10:11]
	s_cbranch_vccnz .LBB0_418
	v_readlane_b32 s8, v247, 19
	v_readlane_b32 s9, v247, 20
	s_mov_b64 s[56:57], s[84:85]
	s_andn2_b64 vcc, exec, s[8:9]
	s_cbranch_vccnz .LBB0_327
	s_load_dwordx2 s[40:41], s[56:57], 0x108
	v_readlane_b32 s2, v246, 27
	v_readlane_b32 s8, v246, 21
	s_add_i32 s2, s2, 2
	v_readlane_b32 s9, v246, 22
	s_and_b64 s[8:9], s[8:9], exec
	s_mov_b32 s6, 0x10b98100
	s_cselect_b32 s6, s6, 0x11c18100
	s_lshl_b64 s[8:9], s[0:1], 21
	s_waitcnt lgkmcnt(0)
	s_add_u32 s42, s40, 0x14958100
	s_mul_hi_i32 s10, s2, 0xc0000
	s_mul_i32 s2, s2, 0xc0000
	s_addc_u32 s43, s41, 0
	s_add_u32 s2, s40, s2
	s_addc_u32 s10, s41, s10
	s_add_u32 s44, s2, 0x7200000
	s_addc_u32 s45, s10, 0
	s_add_u32 s2, s40, s6
	s_addc_u32 s6, s41, 0
	s_add_u32 s46, s2, s8
	s_addc_u32 s47, s6, s9
	s_add_u32 s8, s40, 0x7bc5000
	s_addc_u32 s9, s41, 0
	v_readlane_b32 s12, v247, 44
	s_mov_b32 s13, s83
	s_bitcmp1_b32 s83, 4
	s_cbranch_scc0 .Lhw_outproj_noprio
	s_setprio 1
.Lhw_outproj_noprio:
	v_and_b32_e32 v177, 63, v194
	v_lshrrev_b32_e32 v178, 6, v194
	v_lshrrev_b32_e32 v160, 2, v194
	v_lshlrev_b32_e32 v160, 11, v160
	v_and_b32_e32 v179, 3, v177
	v_bfe_u32 v180, v177, 4, 2
	v_xor_b32_e32 v179, v179, v180
	v_lshl_add_u32 v160, v179, 4, v160
	v_add_u32_e32 v161, 0x20000, v160
	v_and_b32_e32 v174, 31, v177
	v_lshrrev_b32_e32 v182, 5, v177
	v_bfe_u32 v183, v174, 2, 2
	v_xor_b32_e32 v184, v182, v183
	v_xor_b32_e32 v185, 2, v184
	v_lshrrev_b32_e32 v186, 1, v178
	v_and_b32_e32 v187, 1, v178
	v_lshl_add_u32 v188, v186, 6, v174
	v_lshl_add_u32 v189, v187, 6, v174
	v_lshlrev_b32_e32 v188, 6, v188
	v_lshlrev_b32_e32 v189, 6, v189
	v_lshl_add_u32 v154, v184, 4, v188
	v_lshl_add_u32 v155, v185, 4, v188
	v_lshl_add_u32 v156, v184, 4, v189
	v_lshl_add_u32 v157, v185, 4, v189
	v_add_u32_e32 v158, 0x2000, v156
	v_add_u32_e32 v159, 0x2000, v157
	v_lshlrev_b32_e32 v190, 6, v186
	v_lshl_add_u32 v190, v182, 2, v190
	v_lshl_add_u32 v191, v187, 6, v174
	v_lshlrev_b32_e32 v192, 12, v190
	v_lshl_add_u32 v162, v191, 2, v192
	v_add_u32_e32 v163, 0x1000, v162
	v_add_u32_e32 v164, 0x2000, v162
	v_add_u32_e32 v165, 0x3000, v162
	v_lshlrev_b32_e32 v166, 2, v191
	v_mul_u32_u24_e32 v167, 0xc000, v187
	v_lshl_add_u32 v167, v190, 2, v167
	v_xor_b32_e32 v168, 16, v177
	v_lshlrev_b32_e32 v168, 2, v168
	v_xor_b32_e32 v169, 8, v177
	v_lshlrev_b32_e32 v169, 2, v169
	v_xor_b32_e32 v171, 4, v177
	v_lshlrev_b32_e32 v171, 2, v171
	v_xor_b32_e32 v172, 2, v177
	v_lshlrev_b32_e32 v172, 2, v172
	v_xor_b32_e32 v173, 1, v177
	v_lshlrev_b32_e32 v173, 2, v173
	v_readfirstlane_b32 s65, v194
	s_nop 0
	s_lshl_b32 s65, s65, 4
	s_add_u32 s65, s65, 16
	s_mov_b32 s16, s83

.Lhw_outproj_exit:
	s_setprio 0
	s_branch .LBB0_327

.LBB0_2297:
	s_lshl_b32 s58, s88, 1
	v_readlane_b32 s0, v246, 25
	v_readlane_b32 s66, v246, 19
	s_cmp_gt_i32 s0, 1
	s_mov_b64 s[0:1], -1
	s_mov_b32 s59, 0x30000
	s_movk_i32 s62, 0xfff
	s_mov_b32 s63, 0x20000
	s_mov_b32 s64, 0xfffffc0
	s_movk_i32 s65, 0x1ff
	v_readlane_b32 s67, v246, 20
	s_cbranch_scc0 .LBB0_2457
	v_readlane_b32 s0, v246, 26
	v_readlane_b32 s10, v247, 19
	s_cmp_eq_u32 s0, 11
	v_readlane_b32 s11, v247, 20
	s_cselect_b64 s[8:9], -1, 0
	s_mov_b64 s[0:1], s[84:85]
	s_andn2_b64 vcc, exec, s[10:11]
	s_cbranch_vccnz .LBB0_2365
	v_cndmask_b32_e64 v0, 0, 1, s[8:9]
	s_load_dwordx2 s[40:41], s[0:1], 0x108
	v_readfirstlane_b32 s2, v0
	s_or_b32 s2, s58, s2
	s_and_b64 s[10:11], s[8:9], exec
	s_cselect_b32 s10, 3, 1
	v_readlane_b32 s11, v246, 27
	s_cselect_b32 s12, 8, 2
	s_add_i32 s10, s11, s10
	s_waitcnt lgkmcnt(0)
	s_add_u32 s42, s40, 0x3000000
	s_addc_u32 s43, s41, 0
	s_add_u32 s13, s40, 0x7bc0000
	s_addc_u32 s14, s41, 0
	s_mul_hi_i32 s11, s10, 0xc0000
	s_mul_i32 s10, s10, 0xc0000
	s_add_u32 s10, s40, s10
	s_addc_u32 s11, s41, s11
	s_add_u32 s44, s10, 0x7200000
	s_mul_hi_i32 s6, s2, 0x580000
	s_mul_i32 s2, s2, 0x580000
	s_addc_u32 s45, s11, 0
	s_add_u32 s2, s40, s2
	s_addc_u32 s6, s41, s6
	s_add_u32 s46, s2, 0xd478100
	s_addc_u32 s47, s6, 0
	v_readlane_b32 s15, v247, 44
	s_mov_b32 s16, s83
	s_lshl_b32 s2, s12, 12
	s_add_u32 s12, s13, s2
	s_addc_u32 s13, s14, 0
	s_bitcmp1_b32 s83, 4
	s_cbranch_scc0 .Lhw_ffndown_noprio
	s_setprio 1
.Lhw_ffndown_noprio:
	v_and_b32_e32 v177, 63, v194
	v_lshrrev_b32_e32 v178, 6, v194
	v_lshrrev_b32_e32 v160, 2, v194
	v_mul_u32_u24_e32 v160, 0x1600, v160
	v_and_b32_e32 v179, 3, v177
	v_bfe_u32 v180, v177, 4, 2
	v_xor_b32_e32 v179, v179, v180
	v_lshl_add_u32 v160, v179, 4, v160
	v_add_u32_e32 v161, 0x58000, v160
	v_and_b32_e32 v174, 31, v177
	v_lshrrev_b32_e32 v182, 5, v177
	v_bfe_u32 v183, v174, 2, 2
	v_xor_b32_e32 v184, v182, v183
	v_xor_b32_e32 v185, 2, v184
	v_lshrrev_b32_e32 v186, 1, v178
	v_and_b32_e32 v187, 1, v178
	v_lshl_add_u32 v188, v186, 6, v174
	v_lshl_add_u32 v189, v187, 6, v174
	v_lshlrev_b32_e32 v188, 6, v188
	v_lshlrev_b32_e32 v189, 6, v189
	v_lshl_add_u32 v154, v184, 4, v188
	v_lshl_add_u32 v155, v185, 4, v188
	v_lshl_add_u32 v156, v184, 4, v189
	v_lshl_add_u32 v157, v185, 4, v189
	v_add_u32_e32 v158, 0x2000, v156
	v_add_u32_e32 v159, 0x2000, v157
	v_lshlrev_b32_e32 v190, 6, v186
	v_lshl_add_u32 v190, v182, 2, v190
	v_lshl_add_u32 v191, v187, 6, v174
	v_lshlrev_b32_e32 v192, 12, v190
	v_lshl_add_u32 v162, v191, 2, v192
	v_add_u32_e32 v163, 0x1000, v162
	v_add_u32_e32 v164, 0x2000, v162
	v_add_u32_e32 v165, 0x3000, v162
	v_lshlrev_b32_e32 v166, 2, v191
	v_mul_u32_u24_e32 v167, 0xc000, v187
	v_lshl_add_u32 v167, v190, 2, v167
	v_xor_b32_e32 v168, 16, v177
	v_lshlrev_b32_e32 v168, 2, v168
	v_xor_b32_e32 v169, 8, v177
	v_lshlrev_b32_e32 v169, 2, v169
	v_xor_b32_e32 v171, 4, v177
	v_lshlrev_b32_e32 v171, 2, v171
	v_xor_b32_e32 v172, 2, v177
	v_lshlrev_b32_e32 v172, 2, v172
	v_xor_b32_e32 v173, 1, v177
	v_lshlrev_b32_e32 v173, 2, v173
	v_readfirstlane_b32 s65, v194
	s_nop 0
	s_lshl_b32 s65, s65, 4
	s_add_u32 s65, s65, 16
	s_mov_b32 s16, s83

.Lhw_ffnup_Dd:
	s_bitcmp1_b32 s83, 4
	s_cbranch_scc0 .Lhw_ffnup_noprio
	s_setprio 1

.Lhw_ffnup_exit:
	s_setprio 0
	s_getpc_b64 s[98:99]
